# gate rows remapped batch-per-XCD; scan->gate becomes an XCD-local barrier, the launch-wide 'all scans done' condition (needed only before the rope table / weight conversions reuse memory) is a counter
# speedup vs baseline: 1.0065x; 1.0065x over previous
.LBB0_308:
	s_waitcnt vmcnt(0)
	v_readfirstlane_b32 s4, v194
	s_cmp_gt_u32 s4, 63
	v_readlane_b32 s77, v242, 9
	v_readlane_b32 s78, v241, 13
	v_readlane_b32 s40, v241, 12
	v_readlane_b32 s41, v241, 4
	s_barrier
	s_cbranch_scc1 .LBB0_362
	v_mbcnt_lo_u32_b32 v0, -1, 0
	v_mbcnt_hi_u32_b32 v0, -1, v0
	s_nop 0
	v_cmp_eq_u32_e32 vcc, 0, v0
	s_and_saveexec_b64 s[6:7], vcc
	s_cbranch_execz .LBB0_361
	v_mov_b32_e32 v0, 0x23ff0
	s_waitcnt vmcnt(0) lgkmcnt(0)
	ds_read_b128 v[0:3], v0
	s_waitcnt lgkmcnt(0)
	v_readfirstlane_b32 s8, v2
	s_nop 0
	s_cmp_eq_u32 s8, 0
	s_cbranch_scc1 .Lfb_slow_1
	v_readfirstlane_b32 s9, v0
	s_cmp_eq_u32 s9, 32
	s_cbranch_scc0 .Lfb_xcd_1
	buffer_inv sc1
	s_getreg_b32 s8, hwreg(HW_REG_XCC_ID, 0, 4)
	s_and_b32 s8, s8, 7
	s_lshl_b32 s8, s8, 8
	s_add_u32 s8, s8, 0x3600
	s_add_u32 s4, s92, 0x510000
	s_addc_u32 s5, s93, 0
	v_mov_b32_e32 v7, 1
	s_bfe_u32 s9, s2, 0x20006
	s_lshl_b32 s9, s9, 2
	s_add_u32 s9, s9, s8
	s_add_u32 s9, s9, 0xe0
	v_mov_b32_e32 v6, s9
	global_atomic_add v6, v7, s[4:5]
	s_bfe_u32 s9, s2, 0x20006
	s_lshl_b32 s9, s9, 2
	s_add_u32 s9, s9, s8
	s_add_u32 s9, s9, 0xe0
	v_mov_b32_e32 v6, s9
	s_mov_b32 s9, 0
.Lfb_gs_1:
	global_load_dword v8, v6, s[4:5] sc1
	s_waitcnt vmcnt(0)
	v_add_u32_e32 v8, -16, v8
	v_cmp_le_i32_e32 vcc, 0, v8
	s_cbranch_vccnz .Lfb_done_1
	s_sleep 1
	s_add_u32 s9, s9, 1
	s_cmp_lt_u32 s9, 0x40000
	s_cbranch_scc1 .Lfb_gs_1
	s_branch .Lfb_done_1

.Lscan_loop:
	s_and_b32 s7, s6, 3
	s_lshl_b32 s7, s7, 12
	v_add_u32_e32 v23, s7, v22
	ds_read_b128 v[32:35], v10 offset:0
	ds_read_b128 v[48:51], v11 offset:0
	ds_read_b128 v[36:39], v10 offset:64
	ds_read_b128 v[52:55], v12 offset:0
	ds_read_b128 v[40:43], v10 offset:128
	ds_read_b128 v[56:59], v13 offset:0
	ds_read_b128 v[44:47], v10 offset:192
	ds_read_b128 v[60:63], v14 offset:0
	ds_read_u16 v80, v23 offset:0
	ds_read_u16 v81, v23 offset:64
	ds_read_u16 v82, v23 offset:128
	ds_read_u16 v83, v23 offset:192
	s_add_u32 s33, s6, 1
	s_min_u32 s33, s33, 31
	s_add_u32 s36, s6, 2
	s_min_u32 s36, s36, 31
	v_readlane_b32 s37, v24, s6
	s_nop 1
	v_mul_f32_e32 v92, s37, v92
	v_mul_f32_e32 v93, s37, v93
	v_mul_f32_e32 v94, s37, v94
	v_mul_f32_e32 v95, s37, v95
	v_mul_f32_e32 v96, s37, v96
	v_mul_f32_e32 v97, s37, v97
	v_mul_f32_e32 v98, s37, v98
	v_mul_f32_e32 v99, s37, v99
	s_waitcnt lgkmcnt(10)
	v_mfma_f32_16x16x32_bf16 v[84:87], v[48:51], v[32:35], 0
	s_waitcnt lgkmcnt(8)
	v_mfma_f32_16x16x32_bf16 v[84:87], v[52:55], v[36:39], v[84:87]
	s_waitcnt lgkmcnt(6)
	v_mfma_f32_16x16x32_bf16 v[84:87], v[56:59], v[40:43], v[84:87]
	s_waitcnt lgkmcnt(4)
	v_mfma_f32_16x16x32_bf16 v[84:87], v[60:63], v[44:47], v[84:87]
	ds_read_b128 v[64:67], v11 offset:32768
	ds_read_b128 v[68:71], v12 offset:32768
	ds_read_b128 v[72:75], v13 offset:32768
	ds_read_b128 v[76:79], v14 offset:32768
	s_waitcnt lgkmcnt(4)
	v_lshlrev_b32_e32 v80, 16, v80
	v_lshlrev_b32_e32 v81, 16, v81
	v_lshlrev_b32_e32 v82, 16, v82
	v_lshlrev_b32_e32 v83, 16, v83
	v_sub_f32_e32 v26, v80, v84
	v_sub_f32_e32 v27, v81, v85
	v_sub_f32_e32 v28, v82, v86
	v_sub_f32_e32 v29, v83, v87
	v_cvt_pk_bf16_f32 v26, v26, v27
	v_cvt_pk_bf16_f32 v27, v28, v29
	ds_write_b64 v20, v[26:27]
	s_lshl_b32 s7, s33, 14
	s_add_u32 s26, s14, s7
	s_addc_u32 s27, s15, 0
	s_add_i32 m0, s30, 0x14000
	s_nop 0
	global_load_lds_dwordx4 v5, s[26:27]
	s_add_i32 m0, s30, 0x14400
	s_nop 0
	global_load_lds_dwordx4 v6, s[26:27]
	s_lshl_b32 s7, s33, 13
	s_add_u32 s28, s18, s7
	s_addc_u32 s29, s19, 0
	s_add_i32 m0, s31, 0x1a000
	s_nop 0
	global_load_lds_dwordx4 v7, s[28:29]
	s_lshl_b32 s7, s36, 14
	s_add_u32 s26, s24, s7
	s_addc_u32 s27, s25, 0
	s_add_u32 s8, s6, 2
	s_and_b32 s8, s8, 3
	s_lshl_b32 s8, s8, 12
	s_add_u32 s8, s8, s32
	s_add_i32 m0, s8, 0x1f400
	s_nop 0
	global_load_lds_dwordx4 v8, s[26:27]
	s_waitcnt vmcnt(10) lgkmcnt(0)
	s_barrier
	ds_read_b128 v[100:103], v19
	ds_read_b128 v[108:111], v15 offset:0
	ds_read_b128 v[112:115], v15 offset:2048
	ds_read_b128 v[104:107], v19 offset:64
	ds_read_b128 v[116:119], v16 offset:0
	ds_read_b128 v[120:123], v16 offset:2048
	ds_read_b128 v[124:127], v17 offset:0
	ds_read_b128 v[128:131], v18 offset:0
	v_mfma_f32_16x16x32_bf16 v[88:91], v[32:35], v[64:67], 0
	v_mfma_f32_16x16x32_bf16 v[88:91], v[36:39], v[68:71], v[88:91]
	v_mfma_f32_16x16x32_bf16 v[88:91], v[40:43], v[72:75], v[88:91]
	v_mfma_f32_16x16x32_bf16 v[88:91], v[44:47], v[76:79], v[88:91]
	s_waitcnt lgkmcnt(6)
	v_mfma_f32_16x16x32_bf16 v[92:95], v[108:111], v[100:103], v[92:95]
	s_waitcnt lgkmcnt(5)
	v_mfma_f32_16x16x32_bf16 v[96:99], v[112:115], v[100:103], v[96:99]
	s_waitcnt lgkmcnt(3)
	v_mfma_f32_16x16x32_bf16 v[92:95], v[116:119], v[104:107], v[92:95]
	s_waitcnt lgkmcnt(2)
	v_mfma_f32_16x16x32_bf16 v[96:99], v[120:123], v[104:107], v[96:99]
	s_waitcnt lgkmcnt(1)
	v_mfma_f32_16x16x32_bf16 v[88:91], v[100:103], v[124:127], v[88:91]
	s_waitcnt lgkmcnt(0)
	v_mfma_f32_16x16x32_bf16 v[88:91], v[104:107], v[128:131], v[88:91]
	s_lshl_b32 s7, s6, 14
	s_add_u32 s28, s24, s7
	s_addc_u32 s29, s25, 0
	s_nop 1
	v_cvt_pk_bf16_f32 v26, v92, v93
	v_cvt_pk_bf16_f32 v27, v94, v95
	v_cvt_pk_bf16_f32 v28, v96, v97
	v_cvt_pk_bf16_f32 v29, v98, v99
	ds_write_b64 v21, v[26:27]
	ds_write_b64 v21, v[28:29] offset:32
	s_lshl_b32 s7, s36, 14
	s_add_u32 s26, s10, s7
	s_addc_u32 s27, s11, 0
	s_add_i32 m0, s30, 0x0
	s_nop 0
	global_load_lds_dwordx4 v3, s[26:27]
	s_add_i32 m0, s30, 0x400
	s_nop 0
	global_load_lds_dwordx4 v4, s[26:27]
	s_lshl_b32 s7, s36, 14
	s_add_u32 s26, s12, s7
	s_addc_u32 s27, s13, 0
	s_add_i32 m0, s30, 0x8000
	s_nop 0
	global_load_lds_dwordx4 v3, s[26:27]
	s_add_i32 m0, s30, 0x8400
	s_nop 0
	global_load_lds_dwordx4 v4, s[26:27]
	v_cvt_pk_bf16_f32 v80, v88, v89
	v_cvt_pk_bf16_f32 v81, v90, v91
	global_store_dwordx2 v9, v[80:81], s[28:29]
	s_add_u32 s6, s6, 1
	s_waitcnt vmcnt(10) lgkmcnt(0)
	s_barrier
	s_and_b32 s7, s6, 3
	s_lshl_b32 s7, s7, 12
	v_add_u32_e32 v23, s7, v22
	ds_read_b128 v[32:35], v10 offset:0
	ds_read_b128 v[48:51], v11 offset:16384
	ds_read_b128 v[36:39], v10 offset:64
	ds_read_b128 v[52:55], v12 offset:16384
	ds_read_b128 v[40:43], v10 offset:128
	ds_read_b128 v[56:59], v13 offset:16384
	ds_read_b128 v[44:47], v10 offset:192
	ds_read_b128 v[60:63], v14 offset:16384
	ds_read_u16 v80, v23 offset:0
	ds_read_u16 v81, v23 offset:64
	ds_read_u16 v82, v23 offset:128
	ds_read_u16 v83, v23 offset:192
	s_add_u32 s33, s6, 1
	s_min_u32 s33, s33, 31
	s_add_u32 s36, s6, 2
	s_min_u32 s36, s36, 31
	v_readlane_b32 s37, v24, s6
	s_nop 1
	v_mul_f32_e32 v92, s37, v92
	v_mul_f32_e32 v93, s37, v93
	v_mul_f32_e32 v94, s37, v94
	v_mul_f32_e32 v95, s37, v95
	v_mul_f32_e32 v96, s37, v96
	v_mul_f32_e32 v97, s37, v97
	v_mul_f32_e32 v98, s37, v98
	v_mul_f32_e32 v99, s37, v99
	s_waitcnt lgkmcnt(10)
	v_mfma_f32_16x16x32_bf16 v[84:87], v[48:51], v[32:35], 0
	s_waitcnt lgkmcnt(8)
	v_mfma_f32_16x16x32_bf16 v[84:87], v[52:55], v[36:39], v[84:87]
	s_waitcnt lgkmcnt(6)
	v_mfma_f32_16x16x32_bf16 v[84:87], v[56:59], v[40:43], v[84:87]
	s_waitcnt lgkmcnt(4)
	v_mfma_f32_16x16x32_bf16 v[84:87], v[60:63], v[44:47], v[84:87]
	ds_read_b128 v[64:67], v11 offset:49152
	ds_read_b128 v[68:71], v12 offset:49152
	ds_read_b128 v[72:75], v13 offset:49152
	ds_read_b128 v[76:79], v14 offset:49152
	s_waitcnt lgkmcnt(4)
	v_lshlrev_b32_e32 v80, 16, v80
	v_lshlrev_b32_e32 v81, 16, v81
	v_lshlrev_b32_e32 v82, 16, v82
	v_lshlrev_b32_e32 v83, 16, v83
	v_sub_f32_e32 v26, v80, v84
	v_sub_f32_e32 v27, v81, v85
	v_sub_f32_e32 v28, v82, v86
	v_sub_f32_e32 v29, v83, v87
	v_cvt_pk_bf16_f32 v26, v26, v27
	v_cvt_pk_bf16_f32 v27, v28, v29
	ds_write_b64 v20, v[26:27]
	s_lshl_b32 s7, s33, 14
	s_add_u32 s26, s14, s7
	s_addc_u32 s27, s15, 0
	s_add_i32 m0, s30, 0x10000
	s_nop 0
	global_load_lds_dwordx4 v5, s[26:27]
	s_add_i32 m0, s30, 0x10400
	s_nop 0
	global_load_lds_dwordx4 v6, s[26:27]
	s_lshl_b32 s7, s33, 13
	s_add_u32 s28, s18, s7
	s_addc_u32 s29, s19, 0
	s_add_i32 m0, s31, 0x18000
	s_nop 0
	global_load_lds_dwordx4 v7, s[28:29]
	s_lshl_b32 s7, s36, 14
	s_add_u32 s26, s24, s7
	s_addc_u32 s27, s25, 0
	s_add_u32 s8, s6, 2
	s_and_b32 s8, s8, 3
	s_lshl_b32 s8, s8, 12
	s_add_u32 s8, s8, s32
	s_add_i32 m0, s8, 0x1f400
	s_nop 0
	global_load_lds_dwordx4 v8, s[26:27]
	s_waitcnt vmcnt(10) lgkmcnt(0)
	s_barrier
	ds_read_b128 v[100:103], v19
	ds_read_b128 v[108:111], v15 offset:16384
	ds_read_b128 v[112:115], v15 offset:18432
	ds_read_b128 v[104:107], v19 offset:64
	ds_read_b128 v[116:119], v16 offset:16384
	ds_read_b128 v[120:123], v16 offset:18432
	ds_read_b128 v[124:127], v17 offset:8192
	ds_read_b128 v[128:131], v18 offset:8192
	v_mfma_f32_16x16x32_bf16 v[88:91], v[32:35], v[64:67], 0
	v_mfma_f32_16x16x32_bf16 v[88:91], v[36:39], v[68:71], v[88:91]
	v_mfma_f32_16x16x32_bf16 v[88:91], v[40:43], v[72:75], v[88:91]
	v_mfma_f32_16x16x32_bf16 v[88:91], v[44:47], v[76:79], v[88:91]
	s_waitcnt lgkmcnt(6)
	v_mfma_f32_16x16x32_bf16 v[92:95], v[108:111], v[100:103], v[92:95]
	s_waitcnt lgkmcnt(5)
	v_mfma_f32_16x16x32_bf16 v[96:99], v[112:115], v[100:103], v[96:99]
	s_waitcnt lgkmcnt(3)
	v_mfma_f32_16x16x32_bf16 v[92:95], v[116:119], v[104:107], v[92:95]
	s_waitcnt lgkmcnt(2)
	v_mfma_f32_16x16x32_bf16 v[96:99], v[120:123], v[104:107], v[96:99]
	s_waitcnt lgkmcnt(1)
	v_mfma_f32_16x16x32_bf16 v[88:91], v[100:103], v[124:127], v[88:91]
	s_waitcnt lgkmcnt(0)
	v_mfma_f32_16x16x32_bf16 v[88:91], v[104:107], v[128:131], v[88:91]
	s_lshl_b32 s7, s6, 14
	s_add_u32 s28, s24, s7
	s_addc_u32 s29, s25, 0
	s_nop 1
	v_cvt_pk_bf16_f32 v26, v92, v93
	v_cvt_pk_bf16_f32 v27, v94, v95
	v_cvt_pk_bf16_f32 v28, v96, v97
	v_cvt_pk_bf16_f32 v29, v98, v99
	ds_write_b64 v21, v[26:27]
	ds_write_b64 v21, v[28:29] offset:32
	s_lshl_b32 s7, s36, 14
	s_add_u32 s26, s10, s7
	s_addc_u32 s27, s11, 0
	s_add_i32 m0, s30, 0x4000
	s_nop 0
	global_load_lds_dwordx4 v3, s[26:27]
	s_add_i32 m0, s30, 0x4400
	s_nop 0
	global_load_lds_dwordx4 v4, s[26:27]
	s_lshl_b32 s7, s36, 14
	s_add_u32 s26, s12, s7
	s_addc_u32 s27, s13, 0
	s_add_i32 m0, s30, 0xc000
	s_nop 0
	global_load_lds_dwordx4 v3, s[26:27]
	s_add_i32 m0, s30, 0xc400
	s_nop 0
	global_load_lds_dwordx4 v4, s[26:27]
	v_cvt_pk_bf16_f32 v80, v88, v89
	v_cvt_pk_bf16_f32 v81, v90, v91
	global_store_dwordx2 v9, v[80:81], s[28:29]
	s_add_u32 s6, s6, 1
	s_waitcnt vmcnt(10) lgkmcnt(0)
	s_barrier
	s_cmp_lt_u32 s6, 32
	s_cbranch_scc1 .Lscan_loop
	s_lshl_b32 s56, s77, 5
	s_and_b32 s57, s40, 3
	s_lshl_b32 s72, s40, 5
	s_waitcnt vmcnt(0)
	v_readfirstlane_b32 s3, v194
	s_cmp_gt_u32 s3, 63
	s_barrier
	s_cbranch_scc1 .LBB0_421
	s_waitcnt vmcnt(2)
	v_mbcnt_lo_u32_b32 v0, -1, 0
	v_mbcnt_hi_u32_b32 v0, -1, v0
	s_nop 0
	v_cmp_eq_u32_e32 vcc, 0, v0
	s_and_saveexec_b64 s[6:7], vcc
	s_cbranch_execz .LBB0_420
	v_mov_b32_e32 v0, 0x23ff0
	s_waitcnt vmcnt(0) lgkmcnt(0)
	ds_read_b128 v[0:3], v0
	s_waitcnt lgkmcnt(0)
	s_add_u32 s4, s92, 0x510000
	s_addc_u32 s5, s93, 0
	v_mov_b32_e32 v6, 0x3e00
	v_mov_b32_e32 v7, 1
	global_atomic_add v6, v7, s[4:5]
	v_readfirstlane_b32 s3, v2
	s_nop 0
	s_cmp_eq_u32 s3, 0
	s_cbranch_scc1 .Lfb_slow_2
	buffer_inv sc1
	v_add_u32_e32 v3, 1, v3
	v_mov_b32_e32 v4, 0x23ffc
	ds_write_b32 v4, v3
	v_mul_lo_u32 v5, v3, v0
	s_getreg_b32 s3, hwreg(HW_REG_XCC_ID, 0, 4)
	s_and_b32 s3, s3, 7
	s_lshl_b32 s3, s3, 8
	s_add_u32 s3, s3, 0x3680
	s_add_u32 s4, s92, 0x510000
	s_addc_u32 s5, s93, 0
	v_mov_b32_e32 v6, s3
	v_mov_b32_e32 v7, 1
	global_atomic_add v6, v7, s[4:5]
	s_mov_b32 s8, 0

.LBB0_400:
	s_andn2_saveexec_b64 s[4:5], s[8:9]
	s_cbranch_execz .LBB0_420
	v_mov_b32_e32 v1, 0x23ff8
	ds_read_b32 v1, v1
	s_waitcnt lgkmcnt(0)
	v_readfirstlane_b32 s3, v1
	s_nop 0
	s_cmp_lg_u32 s3, 0
	s_cbranch_scc1 .Lxloc_2
	s_mov_b64 s[8:9], exec
	buffer_wbl2 sc1
	s_waitcnt lgkmcnt(0)
	s_waitcnt vmcnt(0)
	v_mbcnt_lo_u32_b32 v1, s8, 0
	v_mbcnt_hi_u32_b32 v1, s9, v1
	v_cmp_eq_u32_e32 vcc, 0, v1
	s_and_saveexec_b64 s[10:11], vcc
	s_cbranch_execz .LBB0_403
	s_bcnt1_i32_b64 s3, s[8:9]
	v_readlane_b32 s4, v240, 24
	v_mov_b32_e32 v2, 0
	v_mov_b32_e32 v3, s3
	v_readlane_b32 s5, v240, 25
	s_nop 4
	global_atomic_add v2, v2, v3, s[4:5] sc0
.LBB0_403:
	s_or_b64 exec, exec, s[10:11]
	s_waitcnt vmcnt(0)
	v_readfirstlane_b32 s3, v2
	v_cvt_f32_u32_e32 v2, v0
	v_sub_u32_e32 v3, 0, v0
	v_add_u32_e32 v1, s3, v1
	v_readlane_b32 s4, v240, 26
	v_rcp_iflag_f32_e32 v2, v2
	v_readlane_b32 s5, v240, 27
	s_mov_b64 s[10:11], -1
	v_mul_f32_e32 v2, 0x4f7ffffe, v2
	v_cvt_u32_f32_e32 v2, v2
	v_mul_lo_u32 v3, v3, v2
	v_mul_hi_u32 v3, v2, v3
	v_add_u32_e32 v2, v2, v3
	v_mul_hi_u32 v2, v1, v2
	v_mul_lo_u32 v3, v2, v0
	v_sub_u32_e32 v3, v1, v3
	v_cmp_ge_u32_e32 vcc, v3, v0
	v_add_u32_e32 v4, 1, v2
	v_add_u32_e32 v1, 1, v1
	v_cndmask_b32_e32 v2, v2, v4, vcc
	v_sub_u32_e32 v4, v3, v0
	v_cndmask_b32_e32 v3, v3, v4, vcc
	v_cmp_ge_u32_e32 vcc, v3, v0
	v_add_u32_e32 v3, 1, v2
	s_nop 0
	v_cndmask_b32_e32 v2, v2, v3, vcc
	v_mul_lo_u32 v3, v0, v2
	v_add_u32_e32 v0, v3, v0
	v_cmp_ne_u32_e32 vcc, v1, v0
	v_mov_b64_e32 v[0:1], s[4:5]
	s_and_saveexec_b64 s[8:9], vcc
	s_cbranch_execz .LBB0_415
	v_readlane_b32 s4, v240, 26
	v_mov_b32_e32 v0, 0
	v_readlane_b32 s5, v240, 27
	s_mov_b64 s[12:13], 0
	s_nop 3
	global_load_dword v1, v0, s[4:5] sc1
	s_waitcnt vmcnt(0)
	v_cmp_eq_u32_e32 vcc, v1, v2
	s_and_saveexec_b64 s[10:11], vcc
	s_cbranch_execz .LBB0_414
	s_mov_b32 s3, 1
	s_branch .LBB0_407

.Lxloc_2:
	s_mov_b64 s[8:9], exec
	v_mbcnt_lo_u32_b32 v0, s8, 0
	v_mbcnt_hi_u32_b32 v0, s9, v0
	v_cmp_eq_u32_e32 vcc, 0, v0
	s_waitcnt vmcnt(0)
	buffer_inv sc1
	s_and_saveexec_b64 s[10:11], vcc
	s_cbranch_execz .LBB0_419
	s_bcnt1_i32_b64 s3, s[8:9]
	v_readlane_b32 s4, v240, 22
	v_mov_b32_e32 v0, 0
	v_mov_b32_e32 v1, s3
	v_readlane_b32 s5, v240, 23
	s_nop 4
	global_atomic_add v0, v1, s[4:5]

.LBB0_421:
	v_readlane_b32 s4, v242, 11
	s_waitcnt lgkmcnt(0)
	s_barrier
	v_mbcnt_lo_u32_b32 v49, -1, 0
	v_mbcnt_hi_u32_b32 v49, -1, v49
	v_readlane_b32 s5, v242, 12
	v_lshlrev_b32_e32 v40, 3, v49
	v_ashrrev_i32_e32 v41, 31, v40
	s_andn2_b64 vcc, exec, s[4:5]
	v_readlane_b32 s38, v241, 2
	v_readlane_b32 s39, v241, 3
	s_cbranch_vccnz .LBB0_424
	s_lshr_b32 s40, s22, 8
	s_lshl_b32 s40, s40, 11
	s_and_b32 s41, s22, 0xff
	s_lshl_b32 s41, s41, 3
	s_add_u32 s40, s40, s41
	s_mov_b32 s41, 0
	s_add_u32 s44, s40, 8
	s_ashr_i32 s4, s40, 8
	s_and_b32 s10, s4, -8
	s_lshl_b32 s4, s40, 8
	s_waitcnt vmcnt(5)
	v_add_u32_e32 v9, 0x200, v40
	s_bfe_u32 s3, s40, 0x50006
	s_and_b32 s4, s4, 0x3f00
	v_and_b32_e32 v8, 0x78, v40
	v_ashrrev_i32_e32 v73, 7, v9
	s_add_u32 s4, s0, s4
	s_waitcnt vmcnt(3)
	v_lshlrev_b32_e32 v4, 2, v8
	s_addc_u32 s5, s1, 0
	s_lshl_b64 s[8:9], s[40:41], 11
	v_lshlrev_b32_e32 v18, 1, v8
	v_add_u32_e32 v8, s10, v73
	s_add_u32 s6, s90, s8
	v_lshl_or_b32 v8, v8, 5, s3
	s_addc_u32 s7, s91, s9
	v_lshlrev_b64 v[16:17], 1, v[40:41]
	v_mov_b32_e32 v19, 0
	v_ashrrev_i32_e32 v9, 31, v8
	v_ashrrev_i32_e32 v72, 7, v40
	s_waitcnt vmcnt(1)
	v_lshl_add_u64 v[12:13], s[6:7], 0, v[16:17]
	v_lshl_add_u64 v[14:15], s[4:5], 0, v[18:19]
	v_lshlrev_b64 v[8:9], 14, v[8:9]
	global_load_dwordx4 v[0:3], v4, s[86:87] offset:16
	s_nop 0
	global_load_dwordx4 v[4:7], v4, s[86:87]
	v_lshl_add_u64 v[20:21], v[14:15], 0, v[8:9]
	global_load_dwordx4 v[8:11], v[12:13], off offset:1024 nt
	global_load_dwordx4 v[32:35], v[12:13], off nt
	v_add_u32_e32 v12, s10, v72
	v_lshl_or_b32 v12, v12, 5, s3
	v_ashrrev_i32_e32 v13, 31, v12
	v_lshlrev_b64 v[12:13], 14, v[12:13]
	v_lshl_add_u64 v[22:23], v[14:15], 0, v[12:13]
	global_load_dwordx4 v[12:15], v[20:21], off nt
	global_load_dwordx4 v[36:39], v[22:23], off nt
	v_lshl_add_u64 v[42:43], s[0:1], 0, v[18:19]
	s_add_u32 s0, s92, s8
	s_addc_u32 s1, s93, s9
	v_lshl_add_u64 v[44:45], s[90:91], 0, v[16:17]
	v_lshl_add_u64 v[16:17], s[0:1], 0, v[16:17]
	s_mov_b64 s[0:1], 0x3000000
	s_ashr_i32 s39, s38, 31
	s_mov_b32 s7, 0
	v_lshl_add_u64 v[46:47], v[16:17], 0, s[0:1]
	s_mov_b64 s[0:1], 0x800
	s_mov_b32 s3, 0x800000
	v_mov_b32_e32 v48, 0x358637bd
	s_mov_b32 s5, s40
.LBB0_423:
	s_waitcnt vmcnt(0)
	v_lshlrev_b32_e32 v50, 16, v39
	v_and_b32_e32 v51, 0xffff0000, v39
	v_lshlrev_b32_e32 v52, 16, v38
	v_and_b32_e32 v53, 0xffff0000, v38
	v_lshlrev_b32_e32 v38, 16, v34
	v_and_b32_e32 v39, 0xffff0000, v34
	v_lshlrev_b32_e32 v60, 16, v35
	v_and_b32_e32 v61, 0xffff0000, v35
	v_mul_f32_e32 v34, 0xbfb8aa3b, v38
	v_mul_f32_e32 v35, 0xbfb8aa3b, v39
	v_exp_f32_e32 v34, v34
	v_exp_f32_e32 v35, v35
	v_lshlrev_b32_e32 v54, 16, v37
	v_and_b32_e32 v55, 0xffff0000, v37
	v_add_f32_e32 v34, 1.0, v34
	v_add_f32_e32 v35, 1.0, v35
	v_rcp_f32_e32 v34, v34
	v_rcp_f32_e32 v35, v35
	v_lshlrev_b32_e32 v58, 16, v36
	v_and_b32_e32 v59, 0xffff0000, v36
	v_lshlrev_b32_e32 v70, 16, v9
	v_pk_mul_f32 v[38:39], v[34:35], v[38:39]
	v_lshlrev_b32_e32 v34, 16, v33
	v_and_b32_e32 v35, 0xffff0000, v33
	v_mul_f32_e32 v33, 0xbfb8aa3b, v34
	v_exp_f32_e32 v33, v33
	v_and_b32_e32 v71, 0xffff0000, v9
	v_mul_f32_e32 v9, 0xbfb8aa3b, v70
	v_exp_f32_e32 v9, v9
	v_add_f32_e32 v33, 1.0, v33
	v_rcp_f32_e32 v56, v33
	v_mul_f32_e32 v33, 0xbfb8aa3b, v35
	v_exp_f32_e32 v33, v33
	s_add_i32 s4, s5, 1
	s_cmp_lt_i32 s4, s44
	s_cselect_b32 s8, s4, s5
	v_add_f32_e32 v33, 1.0, v33
	v_rcp_f32_e32 v57, v33
	s_ashr_i32 s5, s8, 8
	v_lshlrev_b32_e32 v66, 16, v14
	v_and_b32_e32 v67, 0xffff0000, v14
	v_pk_mul_f32 v[56:57], v[56:57], v[34:35]
	v_lshlrev_b32_e32 v34, 16, v32
	v_and_b32_e32 v35, 0xffff0000, v32
	v_mul_f32_e32 v32, 0xbfb8aa3b, v34
	v_mul_f32_e32 v33, 0xbfb8aa3b, v35
	v_exp_f32_e32 v32, v32
	v_exp_f32_e32 v33, v33
	v_lshlrev_b32_e32 v14, 16, v10
	v_add_f32_e32 v9, 1.0, v9
	v_add_f32_e32 v32, 1.0, v32
	v_add_f32_e32 v33, 1.0, v33
	v_rcp_f32_e32 v32, v32
	v_rcp_f32_e32 v33, v33
	s_and_b32 s5, s5, -8
	v_rcp_f32_e32 v80, v9
	v_mul_f32_e32 v9, 0xbfb8aa3b, v71
	v_pk_mul_f32 v[36:37], v[32:33], v[34:35]
	v_mul_f32_e32 v32, 0xbfb8aa3b, v60
	v_mul_f32_e32 v33, 0xbfb8aa3b, v61
	v_exp_f32_e32 v32, v32
	v_exp_f32_e32 v33, v33
	v_lshlrev_b32_e32 v34, 16, v15
	v_and_b32_e32 v35, 0xffff0000, v15
	v_add_f32_e32 v32, 1.0, v32
	v_add_f32_e32 v33, 1.0, v33
	v_rcp_f32_e32 v32, v32
	v_rcp_f32_e32 v33, v33
	v_and_b32_e32 v15, 0xffff0000, v10
	v_mul_f32_e32 v10, 0xbfb8aa3b, v14
	s_bfe_u32 s10, s8, 0x50006
	v_pk_mul_f32 v[60:61], v[32:33], v[60:61]
	v_lshlrev_b32_e32 v32, 16, v11
	v_and_b32_e32 v33, 0xffff0000, v11
	v_mul_f32_e32 v11, 0xbfb8aa3b, v15
	v_add_u32_e32 v16, s5, v72
	v_add_u32_e32 v26, s5, v73
	v_exp_f32_e32 v10, v10
	v_exp_f32_e32 v11, v11
	v_exp_f32_e32 v9, v9
	s_lshl_b32 s6, s8, 8
	v_lshl_or_b32 v16, v16, 5, s10
	v_lshl_or_b32 v26, v26, 5, s10
	s_and_b32 s6, s6, 0x3f00
	s_ashr_i32 s9, s8, 31
	v_ashrrev_i32_e32 v17, 31, v16
	v_ashrrev_i32_e32 v27, 31, v26
	s_lshl_b64 s[8:9], s[8:9], 11
	v_lshl_add_u64 v[24:25], v[42:43], 0, s[6:7]
	v_lshlrev_b64 v[16:17], 14, v[16:17]
	v_lshlrev_b64 v[26:27], 14, v[26:27]
	v_lshl_add_u64 v[28:29], v[44:45], 0, s[8:9]
	v_lshl_add_u64 v[16:17], v[24:25], 0, v[16:17]
	v_lshl_add_u64 v[24:25], v[24:25], 0, v[26:27]
	v_add_f32_e32 v10, 1.0, v10
	v_add_f32_e32 v11, 1.0, v11
	v_add_f32_e32 v9, 1.0, v9
	global_load_dwordx4 v[16:19], v[16:17], off nt
	s_nop 0
	global_load_dwordx4 v[20:23], v[28:29], off nt
	s_nop 0
	global_load_dwordx4 v[24:27], v[24:25], off nt
	s_nop 0
	global_load_dwordx4 v[28:31], v[28:29], off offset:1024 nt
	v_rcp_f32_e32 v10, v10
	v_rcp_f32_e32 v11, v11
	v_rcp_f32_e32 v81, v9
	v_mov_b32_e32 v83, v59
	v_pk_mul_f32 v[68:69], v[54:55], v[54:55]
	v_pk_mul_f32 v[14:15], v[10:11], v[14:15]
	v_lshlrev_b32_e32 v10, 16, v13
	v_and_b32_e32 v11, 0xffff0000, v13
	v_pk_mul_f32 v[70:71], v[80:81], v[70:71]
	v_lshlrev_b32_e32 v80, 16, v12
	v_and_b32_e32 v81, 0xffff0000, v12
	v_lshlrev_b32_e32 v12, 16, v8
	v_and_b32_e32 v13, 0xffff0000, v8
	v_mul_f32_e32 v8, 0xbfb8aa3b, v12
	v_mul_f32_e32 v9, 0xbfb8aa3b, v13
	v_exp_f32_e32 v8, v8
	v_exp_f32_e32 v9, v9
	v_mov_b32_e32 v82, v81
	v_pk_mul_f32 v[78:79], v[10:11], v[10:11]
	v_add_f32_e32 v8, 1.0, v8
	v_add_f32_e32 v9, 1.0, v9
	v_rcp_f32_e32 v8, v8
	v_rcp_f32_e32 v9, v9
	v_pk_mul_f32 v[82:83], v[82:83], v[82:83]
	v_pk_mul_f32 v[64:65], v[52:53], v[52:53]
	v_pk_mul_f32 v[76:77], v[66:67], v[66:67]
	v_pk_mul_f32 v[8:9], v[8:9], v[12:13]
	v_mov_b32_e32 v12, v80
	v_mov_b32_e32 v13, v58
	v_pk_fma_f32 v[12:13], v[12:13], v[12:13], v[82:83]
	v_mov_b32_e32 v82, v78
	v_mov_b32_e32 v83, v68
	v_pk_add_f32 v[12:13], v[82:83], v[12:13]
	v_mov_b32_e32 v68, v79
	v_pk_add_f32 v[12:13], v[68:69], v[12:13]
	v_mov_b32_e32 v68, v76
	v_mov_b32_e32 v69, v64
	v_pk_mul_f32 v[62:63], v[50:51], v[50:51]
	v_pk_mul_f32 v[74:75], v[34:35], v[34:35]
	v_pk_add_f32 v[12:13], v[68:69], v[12:13]
	v_mov_b32_e32 v64, v77
	v_pk_add_f32 v[12:13], v[64:65], v[12:13]
	v_mov_b32_e32 v64, v74
	v_mov_b32_e32 v65, v62
	v_pk_add_f32 v[12:13], v[64:65], v[12:13]
	v_mov_b32_e32 v62, v75
	v_pk_add_f32 v[12:13], v[62:63], v[12:13]
	ds_bpermute_b32 v63, v195, v13
	ds_bpermute_b32 v62, v195, v12
	s_brev_b32 s6, 60
	s_cmp_ge_i32 s4, s44
	s_mov_b32 s5, s4
	s_waitcnt lgkmcnt(0)
	v_pk_add_f32 v[12:13], v[12:13], v[62:63]
	ds_bpermute_b32 v63, v196, v13
	ds_bpermute_b32 v62, v196, v12
	s_waitcnt lgkmcnt(0)
	v_pk_add_f32 v[12:13], v[12:13], v[62:63]
	ds_bpermute_b32 v63, v197, v13
	ds_bpermute_b32 v62, v197, v12
	s_waitcnt lgkmcnt(0)
	v_pk_add_f32 v[12:13], v[12:13], v[62:63]
	ds_bpermute_b32 v63, v161, v13
	ds_bpermute_b32 v62, v161, v12
	s_waitcnt lgkmcnt(0)
	v_pk_add_f32 v[12:13], v[12:13], v[62:63]
	s_nop 0
	v_pk_fma_f32 v[12:13], v[12:13], s[6:7], v[48:49] op_sel_hi:[1,0,0]
	s_nop 0
	v_mul_f32_e32 v41, 0x4b800000, v13
	v_cmp_gt_f32_e64 s[42:43], s3, v13
	v_cmp_gt_f32_e32 vcc, s3, v12
	s_nop 0
	v_cndmask_b32_e64 v13, v13, v41, s[42:43]
	v_rsq_f32_e32 v13, v13
	s_nop 0
	v_mul_f32_e32 v41, 0x45800000, v13
	v_cndmask_b32_e64 v62, v13, v41, s[42:43]
	v_mul_f32_e32 v13, 0x4b800000, v12
	v_cndmask_b32_e32 v12, v12, v13, vcc
	v_rsq_f32_e32 v12, v12
	v_pk_mul_f32 v[58:59], v[62:63], v[58:59] op_sel_hi:[0,1]
	v_pk_mul_f32 v[54:55], v[62:63], v[54:55] op_sel_hi:[0,1]
	v_pk_mul_f32 v[52:53], v[62:63], v[52:53] op_sel_hi:[0,1]
	v_pk_mul_f32 v[50:51], v[62:63], v[50:51] op_sel_hi:[0,1]
	v_pk_mul_f32 v[58:59], v[4:5], v[58:59]
	v_pk_mul_f32 v[54:55], v[6:7], v[54:55]
	v_pk_mul_f32 v[52:53], v[0:1], v[52:53]
	v_pk_mul_f32 v[50:51], v[2:3], v[50:51]
	v_pk_mul_f32 v[36:37], v[36:37], v[58:59]
	v_pk_mul_f32 v[54:55], v[56:57], v[54:55]
	v_pk_mul_f32 v[38:39], v[38:39], v[52:53]
	v_pk_mul_f32 v[50:51], v[60:61], v[50:51]
	v_cvt_pk_bf16_f32 v36, v36, v37
	v_cvt_pk_bf16_f32 v37, v54, v55
	v_cvt_pk_bf16_f32 v38, v38, v39
	v_cvt_pk_bf16_f32 v39, v50, v51
	v_mul_f32_e32 v13, 0x45800000, v12
	global_store_dwordx4 v[46:47], v[36:39], off
	s_nop 1
	v_cndmask_b32_e32 v36, v12, v13, vcc
	v_pk_mul_f32 v[12:13], v[36:37], v[80:81] op_sel_hi:[0,1]
	v_pk_mul_f32 v[12:13], v[4:5], v[12:13]
	v_pk_mul_f32 v[10:11], v[36:37], v[10:11] op_sel_hi:[0,1]
	v_pk_mul_f32 v[8:9], v[8:9], v[12:13]
	v_pk_mul_f32 v[12:13], v[36:37], v[66:67] op_sel_hi:[0,1]
	v_pk_mul_f32 v[12:13], v[0:1], v[12:13]
	v_pk_mul_f32 v[34:35], v[36:37], v[34:35] op_sel_hi:[0,1]
	v_pk_mul_f32 v[12:13], v[14:15], v[12:13]
	v_mul_f32_e32 v14, 0xbfb8aa3b, v32
	v_mul_f32_e32 v15, 0xbfb8aa3b, v33
	v_exp_f32_e32 v14, v14
	v_exp_f32_e32 v15, v15
	v_pk_mul_f32 v[10:11], v[6:7], v[10:11]
	v_pk_mul_f32 v[34:35], v[2:3], v[34:35]
	v_add_f32_e32 v14, 1.0, v14
	v_add_f32_e32 v15, 1.0, v15
	v_rcp_f32_e32 v14, v14
	v_rcp_f32_e32 v15, v15
	v_pk_mul_f32 v[10:11], v[70:71], v[10:11]
	v_cvt_pk_bf16_f32 v8, v8, v9
	v_cvt_pk_bf16_f32 v9, v10, v11
	v_pk_mul_f32 v[14:15], v[14:15], v[32:33]
	v_cvt_pk_bf16_f32 v10, v12, v13
	v_pk_mul_f32 v[14:15], v[14:15], v[34:35]
	s_waitcnt vmcnt(3)
	v_mov_b64_e32 v[34:35], v[22:23]
	v_cvt_pk_bf16_f32 v11, v14, v15
	global_store_dwordx4 v[46:47], v[8:11], off offset:1024
	v_mov_b64_e32 v[38:39], v[18:19]
	s_waitcnt vmcnt(3)
	v_mov_b64_e32 v[12:13], v[24:25]
	s_waitcnt vmcnt(2)
	v_mov_b64_e32 v[8:9], v[28:29]
	v_lshl_add_u64 v[46:47], v[46:47], 0, s[0:1]
	v_mov_b64_e32 v[32:33], v[20:21]
	v_mov_b64_e32 v[10:11], v[30:31]
	v_mov_b64_e32 v[36:37], v[16:17]
	v_mov_b64_e32 v[14:15], v[26:27]
	s_cbranch_scc0 .LBB0_423
.LBB0_424:
	v_readfirstlane_b32 s4, v194
	s_cmp_gt_u32 s4, 63
	s_cbranch_scc1 .Lgc_skip
	s_add_u32 s4, s92, 0x510000
	s_addc_u32 s5, s93, 0
	v_mov_b32_e32 v0, 0x3e00
	s_mov_b32 s8, 0
.Lgc_spin:
	global_load_dword v1, v0, s[4:5] sc1
	s_waitcnt vmcnt(0)
	v_readfirstlane_b32 s9, v1
	s_cmp_ge_u32 s9, 0x100
	s_cbranch_scc1 .Lgc_skip
	s_sleep 1
	s_add_u32 s8, s8, 1
	s_cmp_lt_u32 s8, 0x40000
	s_cbranch_scc1 .Lgc_spin
.Lgc_skip:
	s_barrier
	s_waitcnt vmcnt(2)
	v_ashrrev_i32_e32 v0, 5, v49
	v_lshl_add_u32 v0, s22, 1, v0
	s_movk_i32 s0, 0x4000
	v_cmp_gt_i32_e32 vcc, s0, v0
	s_and_saveexec_b64 s[0:1], vcc
	s_cbranch_execz .LBB0_427
	v_and_b32_e32 v7, 31, v49
	v_lshlrev_b32_e32 v1, 2, v7
	s_getpc_b64 s[4:5]
	s_add_u32 s4, s4, _ZL9ROPE_FREQ@rel32@lo+4
	s_addc_u32 s5, s5, _ZL9ROPE_FREQ@rel32@hi+12
	global_load_dword v6, v1, s[4:5]
	v_ashrrev_i32_e32 v1, 31, v0
	v_lshlrev_b64 v[4:5], 8, v[0:1]
	s_lshl_b32 s6, s94, 4
	v_lshl_or_b32 v4, v7, 3, v4
	v_mov_b32_e32 v2, s74
	v_mov_b32_e32 v3, s75
	s_ashr_i32 s7, s6, 31
	v_lshl_add_u64 v[4:5], s[92:93], 0, v[4:5]
	s_mov_b64 s[4:5], 0x800000
	s_mov_b32 s14, 0x6dc9c883
	v_lshl_add_u64 v[2:3], v[0:1], 2, v[2:3]
	s_lshl_b64 s[8:9], s[6:7], 2
	v_lshl_add_u64 v[4:5], v[4:5], 0, s[4:5]
	s_lshl_b64 s[10:11], s[6:7], 8
	s_mov_b64 s[12:13], 0
	s_mov_b32 s15, 0x3fc45f30
	s_movk_i32 s3, 0x3fff

.LBB0_949:
	s_waitcnt vmcnt(0)
	v_readfirstlane_b32 s0, v194
	s_cmp_gt_u32 s0, 63
	s_waitcnt vmcnt(0)
	s_barrier
	s_cbranch_scc1 .LBB0_1003
	v_mbcnt_lo_u32_b32 v0, -1, 0
	v_mbcnt_hi_u32_b32 v0, -1, v0
	s_nop 0
	v_cmp_eq_u32_e32 vcc, 0, v0
	s_and_saveexec_b64 s[0:1], vcc
	s_cbranch_execz .LBB0_1002
	v_mov_b32_e32 v20, 0x23ff0
	s_waitcnt vmcnt(0) lgkmcnt(0)
	ds_read_b128 v[20:23], v20
	s_waitcnt lgkmcnt(0)
	v_readfirstlane_b32 s3, v22
	s_nop 0
	s_cmp_eq_u32 s3, 0
	s_cbranch_scc1 .Lfb_slow_6
	v_readfirstlane_b32 s8, v20
	s_cmp_eq_u32 s8, 32
	s_cbranch_scc0 .Lfb_xcd_6
	buffer_inv sc1
	s_getreg_b32 s3, hwreg(HW_REG_XCC_ID, 0, 4)
	s_and_b32 s3, s3, 7
	s_lshl_b32 s3, s3, 8
	s_add_u32 s3, s3, 0x3600
	s_add_u32 s4, s92, 0x510000
	s_addc_u32 s5, s93, 0
	v_mov_b32_e32 v27, 1
	s_bfe_u32 s8, s2, 0x20006
	s_lshl_b32 s8, s8, 2
	s_add_u32 s8, s8, s3
	s_add_u32 s8, s8, 0xe0
	v_mov_b32_e32 v26, s8
	global_atomic_add v26, v27, s[4:5]
	s_bfe_u32 s8, s2, 0x20006
	s_lshl_b32 s8, s8, 2
	s_add_u32 s8, s8, s3
	s_add_u32 s8, s8, 0xe0
	v_mov_b32_e32 v26, s8
	s_mov_b32 s8, 0
.Lfb_gs_6:
	global_load_dword v28, v26, s[4:5] sc1
	s_waitcnt vmcnt(0)
	v_add_u32_e32 v28, -24, v28
	v_cmp_le_i32_e32 vcc, 0, v28
	s_cbranch_vccnz .Lfb_done_6
	s_sleep 1
	s_add_u32 s8, s8, 1
	s_cmp_lt_u32 s8, 0x40000
	s_cbranch_scc1 .Lfb_gs_6
	s_branch .Lfb_done_6

.Lfb_gs_8:
	global_load_dword v28, v26, s[4:5] sc1
	global_load_dword v25, v24, s[4:5] sc1
	s_waitcnt vmcnt(0)
	v_add_u32_e32 v28, -12, v28
	v_add_u32_e32 v25, -32, v25
	v_min_i32_e32 v28, v28, v25
	v_cmp_le_i32_e32 vcc, 0, v28
	s_cbranch_vccnz .Lfb_done_8
	s_sleep 1
	s_add_u32 s8, s8, 1
	s_cmp_lt_u32 s8, 0x40000
	s_cbranch_scc1 .Lfb_gs_8
	s_branch .Lfb_done_8
